# LRU final pass: depthwise conv loads batched (2 waits instead of 35 serialized guarded loads)
# speedup vs baseline: 1.0499x; 1.0127x over previous
; __device__ __forceinline__ unsigned cvt_pk_bf16(float lo, float hi) { f32x2_t v = {lo, hi}; bf2_t r = __builtin_convertvector(v, bf2_t); return __builtin_bit_cast(unsigned, r); }
; template <bool FINAL>
; __device__ __forceinline__ void lru_item(const Ctx& C, int l, int item) {
;     ...
;     bf16x8 Bw[2][4][2];
; #pragma unroll
;         for (int ty = 0; ty < 2; ++ty)
; #pragma unroll
;             for (int ks = 0; ks < 2; ++ks) {
;                 const float* wp = (ty ? C.P->in[9] : C.P->in[7]) + ((size_t)((l * 2 + z) * 4 + n) * 64 + 32 * ks + 8 * quad) * 64 + fr;
;                 asm volatile("" : "+v"(wp));
;                 float f[4][8];
; #pragma unroll
;                 for (int dt = 0; dt < 4; ++dt)
; #pragma unroll
;                     for (int e = 0; e < 8; ++e) f[dt][e] = wp[e * 64 + 16 * dt];
; #pragma unroll
;                 for (int dt = 0; dt < 4; ++dt) {
;                     union { bf16x8 v; unsigned u[4]; } t_; t_.u[0] = cvt_pk_bf16(f[dt][0], f[dt][1]); t_.u[1] = cvt_pk_bf16(f[dt][2], f[dt][3]); t_.u[2] = cvt_pk_bf16(f[dt][4], f[dt][5]); t_.u[3] = cvt_pk_bf16(f[dt][6], f[dt][7]); Bw[ty][dt][ks] = t_.v; }
;                 asm volatile("" ::: "memory");
;             }
;     {
;         int ch = tid & 255; asm volatile("" : "+v"(ch)); const int hf = tid >> 8;
;         const float w0 = C.P->in[5][(l * 4 + 0) * 256 + ch], w1 = C.P->in[5][(l * 4 + 1) * 256 + ch], w2 = C.P->in[5][(l * 4 + 2) * 256 + ch], w3 = C.P->in[5][(l * 4 + 3) * 256 + ch], cb = C.P->in[6][l * 256 + ch];
.LBB0_650:
	v_mov_b64_e32 v[0:1], v[78:79]
	flat_load_dword v6, v[0:1]
	flat_load_dword v7, v[0:1] offset:256
	flat_load_dword v8, v[0:1] offset:64
	flat_load_dword v9, v[0:1] offset:320
	flat_load_dword v10, v[0:1] offset:128
	flat_load_dword v11, v[0:1] offset:384
	flat_load_dword v12, v[0:1] offset:448
	flat_load_dword v13, v[0:1] offset:192
	flat_load_dword v20, v[0:1] offset:512
	flat_load_dword v21, v[0:1] offset:768
	flat_load_dword v18, v[0:1] offset:576
	flat_load_dword v19, v[0:1] offset:832
	flat_load_dword v15, v[0:1] offset:640
	flat_load_dword v17, v[0:1] offset:896
	flat_load_dword v14, v[0:1] offset:960
	flat_load_dword v16, v[0:1] offset:704
	flat_load_dword v28, v[0:1] offset:1024
	flat_load_dword v29, v[0:1] offset:1280
	flat_load_dword v26, v[0:1] offset:1088
	flat_load_dword v27, v[0:1] offset:1344
	flat_load_dword v23, v[0:1] offset:1152
	flat_load_dword v25, v[0:1] offset:1408
	flat_load_dword v22, v[0:1] offset:1472
	flat_load_dword v24, v[0:1] offset:1216
	flat_load_dword v37, v[0:1] offset:1536
	flat_load_dword v39, v[0:1] offset:1792
	flat_load_dword v34, v[0:1] offset:1600
	flat_load_dword v35, v[0:1] offset:1856
	flat_load_dword v31, v[0:1] offset:1664
	flat_load_dword v33, v[0:1] offset:1920
	flat_load_dword v30, v[0:1] offset:1984
	flat_load_dword v32, v[0:1] offset:1728
	v_mov_b64_e32 v[0:1], v[80:81]
	flat_load_dword v36, v[0:1]
	flat_load_dword v38, v[0:1] offset:256
	flat_load_dword v40, v[0:1] offset:64
	flat_load_dword v41, v[0:1] offset:320
	flat_load_dword v42, v[0:1] offset:128
	flat_load_dword v43, v[0:1] offset:384
	flat_load_dword v44, v[0:1] offset:448
	flat_load_dword v45, v[0:1] offset:192
	flat_load_dword v52, v[0:1] offset:512
	flat_load_dword v53, v[0:1] offset:768
	flat_load_dword v50, v[0:1] offset:576
	flat_load_dword v51, v[0:1] offset:832
	flat_load_dword v47, v[0:1] offset:640
	flat_load_dword v49, v[0:1] offset:896
	flat_load_dword v46, v[0:1] offset:960
	flat_load_dword v48, v[0:1] offset:704
	flat_load_dword v60, v[0:1] offset:1024
	flat_load_dword v61, v[0:1] offset:1280
	flat_load_dword v58, v[0:1] offset:1088
	flat_load_dword v59, v[0:1] offset:1344
	flat_load_dword v55, v[0:1] offset:1152
	flat_load_dword v57, v[0:1] offset:1408
	flat_load_dword v54, v[0:1] offset:1472
	flat_load_dword v56, v[0:1] offset:1216
	flat_load_dword v71, v[0:1] offset:1536
	flat_load_dword v73, v[0:1] offset:1792
	flat_load_dword v68, v[0:1] offset:1600
	flat_load_dword v69, v[0:1] offset:1856
	flat_load_dword v63, v[0:1] offset:1664
	flat_load_dword v67, v[0:1] offset:1920
	flat_load_dword v62, v[0:1] offset:1984
	flat_load_dword v66, v[0:1] offset:1728
	v_mov_b64_e32 v[0:1], v[82:83]
	flat_load_dword v70, v[0:1]
	flat_load_dword v72, v[0:1] offset:256
	flat_load_dword v74, v[0:1] offset:64
	flat_load_dword v75, v[0:1] offset:320
	flat_load_dword v76, v[0:1] offset:128
	flat_load_dword v77, v[0:1] offset:384
	flat_load_dword v104, v[0:1] offset:448
	flat_load_dword v105, v[0:1] offset:192
	flat_load_dword v174, v[0:1] offset:512
	flat_load_dword v175, v[0:1] offset:768
	flat_load_dword v110, v[0:1] offset:576
	flat_load_dword v111, v[0:1] offset:832
	flat_load_dword v107, v[0:1] offset:640
	flat_load_dword v109, v[0:1] offset:896
	flat_load_dword v106, v[0:1] offset:960
	flat_load_dword v108, v[0:1] offset:704
	flat_load_dword v196, v[0:1] offset:1024
	flat_load_dword v197, v[0:1] offset:1280
	flat_load_dword v194, v[0:1] offset:1088
	flat_load_dword v195, v[0:1] offset:1344
	flat_load_dword v177, v[0:1] offset:1152
	flat_load_dword v193, v[0:1] offset:1408
	flat_load_dword v176, v[0:1] offset:1472
	flat_load_dword v192, v[0:1] offset:1216
	flat_load_dword v205, v[0:1] offset:1536
	flat_load_dword v207, v[0:1] offset:1792
	flat_load_dword v202, v[0:1] offset:1600
	flat_load_dword v203, v[0:1] offset:1856
	flat_load_dword v199, v[0:1] offset:1664
	flat_load_dword v201, v[0:1] offset:1920
	flat_load_dword v198, v[0:1] offset:1984
	flat_load_dword v200, v[0:1] offset:1728
	v_mov_b64_e32 v[0:1], v[84:85]
	flat_load_dword v204, v[0:1]
	flat_load_dword v206, v[0:1] offset:256
	flat_load_dword v208, v[0:1] offset:64
	flat_load_dword v209, v[0:1] offset:320
	flat_load_dword v210, v[0:1] offset:128
	flat_load_dword v211, v[0:1] offset:384
	flat_load_dword v212, v[0:1] offset:448
	flat_load_dword v213, v[0:1] offset:192
	flat_load_dword v232, v[0:1] offset:512
	flat_load_dword v233, v[0:1] offset:768
	flat_load_dword v230, v[0:1] offset:576
	flat_load_dword v231, v[0:1] offset:832
	flat_load_dword v215, v[0:1] offset:640
	flat_load_dword v229, v[0:1] offset:896
	flat_load_dword v214, v[0:1] offset:960
	flat_load_dword v228, v[0:1] offset:704
	flat_load_dword v240, v[0:1] offset:1024
	flat_load_dword v241, v[0:1] offset:1280
	flat_load_dword v238, v[0:1] offset:1088
	flat_load_dword v239, v[0:1] offset:1344
	flat_load_dword v235, v[0:1] offset:1152
	flat_load_dword v237, v[0:1] offset:1408
	flat_load_dword v234, v[0:1] offset:1472
	flat_load_dword v236, v[0:1] offset:1216
	flat_load_dword v248, v[0:1] offset:1536
	flat_load_dword v249, v[0:1] offset:1792
	flat_load_dword v246, v[0:1] offset:1600
	flat_load_dword v247, v[0:1] offset:1856
	flat_load_dword v243, v[0:1] offset:1664
	flat_load_dword v245, v[0:1] offset:1920
	flat_load_dword v242, v[0:1] offset:1984
	flat_load_dword v244, v[0:1] offset:1728
	v_mov_b32_e32 v4, v99
	v_readlane_b32 s0, v254, 63
	v_readlane_b32 s78, v251, 14
	v_readlane_b32 s79, v251, 15
	v_readlane_b32 s80, v251, 16
	v_readlane_b32 s81, v251, 17
	v_add_u32_e32 v0, s0, v4
	v_ashrrev_i32_e32 v1, 31, v0
	v_lshl_add_u64 v[2:3], v[0:1], 2, s[78:79]
	v_add_u32_e32 v0, s40, v0
; __device__ __forceinline__ bf16_t f2bf(float f) { return (bf16_t)(cvt_pk_bf16(f, 0.f) & 0xffffu); }
; __device__ __forceinline__ float bf2f(bf16_t b) { return __uint_as_float(((unsigned)b) << 16); }
; template <bool FINAL>
; __device__ __forceinline__ void lru_item(const Ctx& C, int l, int item) {
;     ...
;         const int tl0 = hf * 32, t0 = c * 64 + tl0;
;         const bf16_t* colp = pb + (size_t)(b * SEQ) * 512 + ch;
;         float xm2 = (t0 - 2 >= 0) ? bf2f(colp[(size_t)(t0 - 2) * 512]) : 0.f, xm1 = (t0 - 1 >= 0) ? bf2f(colp[(size_t)(t0 - 1) * 512]) : 0.f, x0 = bf2f(colp[(size_t)t0 * 512]);
; #pragma unroll 1
;         for (int k8 = 0; k8 < 4; ++k8) { float xn[8];
; #pragma unroll
;             for (int k = 0; k < 8; ++k) { const int t = t0 + k8 * 8 + k + 1; xn[k] = (t < SEQ) ? bf2f(colp[(size_t)t * 512]) : 0.f; }
; #pragma unroll
;             for (int k = 0; k < 8; ++k) { xc[(tl0 + k8 * 8 + k) * XCP + ch] = f2bf(cb + w0 * xm2 + w1 * xm1 + w2 * x0 + w3 * xn[k]); xm2 = xm1; xm1 = x0; x0 = xn[k]; } }
	global_load_dword v162, v[2:3], off
	global_load_dword v163, v[2:3], off offset:1024
	global_load_dword v164, v[2:3], off offset:2048
	global_load_dword v165, v[2:3], off offset:3072
	v_ashrrev_i32_e32 v1, 31, v0
	v_lshl_add_u64 v[0:1], v[0:1], 2, s[80:81]
	global_load_dword v166, v[0:1], off
	s_lshl_b32 s0, s48, 6
	s_and_b32 s0, s0, 0xfffff000
	s_ashr_i32 s1, s0, 31
	s_and_b32 s51, s48, 63
	s_lshl_b64 s[0:1], s[0:1], 10
	s_add_u32 s0, s10, s0
	s_addc_u32 s1, s11, s1
	v_lshl_add_u32 v183, s51, 6, v86
	v_ashrrev_i32_e32 v5, 31, v4
	v_lshl_add_u64 v[0:1], v[4:5], 1, s[0:1]
	v_lshl_add_u32 v64, v4, 1, v142
	s_and_b32 s0, s47, 63
	s_lshl_b32 s49, s0, 6
	s_and_b32 s8, s46, 0xfffff000
	s_mov_b32 s66, 0x358637bd
	s_mov_b64 s[22:23], 0x1000
	s_mov_b64 s[30:31], 0x2000
	v_add_u32_e32 v2, 2, v183
	v_mov_b32_e32 v3, 0
	v_lshlrev_b64 v[2:3], 10, v[2:3]
	v_lshl_add_u64 v[2:3], v[2:3], 0, v[0:1]
	global_load_ushort v4, v[2:3], off offset:-4096
	global_load_ushort v5, v[2:3], off offset:-3072
	global_load_ushort v167, v[2:3], off offset:-2048
	global_load_ushort v168, v[2:3], off offset:-1024
	global_load_ushort v169, v[2:3], off
	global_load_ushort v170, v[2:3], off offset:1024
	global_load_ushort v171, v[2:3], off offset:2048
	global_load_ushort v172, v[2:3], off offset:3072
	v_lshl_add_u64 v[2:3], v[2:3], 0, s[30:31]
	global_load_ushort v173, v[2:3], off offset:-4096
	global_load_ushort v178, v[2:3], off offset:-3072
	global_load_ushort v179, v[2:3], off offset:-2048
	global_load_ushort v180, v[2:3], off offset:-1024
	global_load_ushort v181, v[2:3], off
	global_load_ushort v188, v[2:3], off offset:1024
	global_load_ushort v189, v[2:3], off offset:2048
	global_load_ushort v190, v[2:3], off offset:3072
	v_lshl_add_u64 v[2:3], v[2:3], 0, s[30:31]
	global_load_ushort v191, v[2:3], off offset:-4096
	global_load_ushort v223, v[2:3], off offset:-3072
	global_load_ushort v250, v[2:3], off offset:-2048
	s_movk_i32 s9, 0xfe0
	v_cmp_eq_u32_e32 vcc, 0, v183
	v_cmp_eq_u32_e64 s[0:1], s9, v183
	s_waitcnt vmcnt(0)
	v_cndmask_b32_e64 v4, v4, 0, vcc
	v_cndmask_b32_e64 v5, v5, 0, vcc
	v_lshlrev_b32_e32 v4, 16, v4
	v_lshlrev_b32_e32 v5, 16, v5
	v_lshlrev_b32_e32 v167, 16, v167
	v_lshlrev_b32_e32 v168, 16, v168
	v_lshlrev_b32_e32 v169, 16, v169
	v_lshlrev_b32_e32 v170, 16, v170
	v_lshlrev_b32_e32 v171, 16, v171
	v_lshlrev_b32_e32 v172, 16, v172
	v_lshlrev_b32_e32 v173, 16, v173
	v_lshlrev_b32_e32 v178, 16, v178
	v_lshlrev_b32_e32 v179, 16, v179
	v_lshlrev_b32_e32 v180, 16, v180
	v_lshlrev_b32_e32 v181, 16, v181
	v_lshlrev_b32_e32 v188, 16, v188
	v_lshlrev_b32_e32 v189, 16, v189
	v_lshlrev_b32_e32 v190, 16, v190
	v_lshlrev_b32_e32 v191, 16, v191
	v_lshlrev_b32_e32 v223, 16, v223
	v_lshlrev_b32_e32 v250, 16, v250
	v_fma_f32 v0, v162, v4, v166
	v_fmac_f32_e32 v0, v163, v5
	v_fmac_f32_e32 v0, v164, v167
	v_fmac_f32_e32 v0, v165, v168
	v_cvt_pk_bf16_f32 v0, v0, v0
	ds_write_b16 v64, v0
	v_fma_f32 v1, v162, v5, v166
	v_fmac_f32_e32 v1, v163, v167
	v_fmac_f32_e32 v1, v164, v168
	v_fmac_f32_e32 v1, v165, v169
	v_cvt_pk_bf16_f32 v1, v1, v1
	ds_write_b16 v64, v1 offset:528
	v_fma_f32 v0, v162, v167, v166
	v_fmac_f32_e32 v0, v163, v168
	v_fmac_f32_e32 v0, v164, v169
	v_fmac_f32_e32 v0, v165, v170
	v_cvt_pk_bf16_f32 v0, v0, v0
	ds_write_b16 v64, v0 offset:1056
	v_fma_f32 v1, v162, v168, v166
	v_fmac_f32_e32 v1, v163, v169
	v_fmac_f32_e32 v1, v164, v170
	v_fmac_f32_e32 v1, v165, v171
	v_cvt_pk_bf16_f32 v1, v1, v1
	ds_write_b16 v64, v1 offset:1584
	v_fma_f32 v0, v162, v169, v166
	v_fmac_f32_e32 v0, v163, v170
	v_fmac_f32_e32 v0, v164, v171
	v_fmac_f32_e32 v0, v165, v172
	v_cvt_pk_bf16_f32 v0, v0, v0
	ds_write_b16 v64, v0 offset:2112
	v_fma_f32 v1, v162, v170, v166
	v_fmac_f32_e32 v1, v163, v171
	v_fmac_f32_e32 v1, v164, v172
	v_fmac_f32_e32 v1, v165, v173
	v_cvt_pk_bf16_f32 v1, v1, v1
	ds_write_b16 v64, v1 offset:2640
	v_fma_f32 v0, v162, v171, v166
	v_fmac_f32_e32 v0, v163, v172
	v_fmac_f32_e32 v0, v164, v173
	v_fmac_f32_e32 v0, v165, v178
	v_cvt_pk_bf16_f32 v0, v0, v0
	ds_write_b16 v64, v0 offset:3168
	v_fma_f32 v1, v162, v172, v166
	v_fmac_f32_e32 v1, v163, v173
	v_fmac_f32_e32 v1, v164, v178
	v_fmac_f32_e32 v1, v165, v179
	v_cvt_pk_bf16_f32 v1, v1, v1
	ds_write_b16 v64, v1 offset:3696
	v_fma_f32 v0, v162, v173, v166
	v_fmac_f32_e32 v0, v163, v178
	v_fmac_f32_e32 v0, v164, v179
	v_fmac_f32_e32 v0, v165, v180
	v_cvt_pk_bf16_f32 v0, v0, v0
	ds_write_b16 v64, v0 offset:4224
	v_fma_f32 v1, v162, v178, v166
	v_fmac_f32_e32 v1, v163, v179
	v_fmac_f32_e32 v1, v164, v180
	v_fmac_f32_e32 v1, v165, v181
	v_cvt_pk_bf16_f32 v1, v1, v1
	ds_write_b16 v64, v1 offset:4752
	v_fma_f32 v0, v162, v179, v166
	v_fmac_f32_e32 v0, v163, v180
	v_fmac_f32_e32 v0, v164, v181
	v_fmac_f32_e32 v0, v165, v188
	v_cvt_pk_bf16_f32 v0, v0, v0
	ds_write_b16 v64, v0 offset:5280
	v_fma_f32 v1, v162, v180, v166
	v_fmac_f32_e32 v1, v163, v181
	v_fmac_f32_e32 v1, v164, v188
	v_fmac_f32_e32 v1, v165, v189
	v_cvt_pk_bf16_f32 v1, v1, v1
	ds_write_b16 v64, v1 offset:5808
	v_fma_f32 v0, v162, v181, v166
	v_fmac_f32_e32 v0, v163, v188
	v_fmac_f32_e32 v0, v164, v189
	v_fmac_f32_e32 v0, v165, v190
	v_cvt_pk_bf16_f32 v0, v0, v0
	ds_write_b16 v64, v0 offset:6336
	v_fma_f32 v1, v162, v188, v166
	v_fmac_f32_e32 v1, v163, v189
	v_fmac_f32_e32 v1, v164, v190
	v_fmac_f32_e32 v1, v165, v191
	v_cvt_pk_bf16_f32 v1, v1, v1
	ds_write_b16 v64, v1 offset:6864
	v_fma_f32 v0, v162, v189, v166
	v_fmac_f32_e32 v0, v163, v190
	v_fmac_f32_e32 v0, v164, v191
	v_fmac_f32_e32 v0, v165, v223
	v_cvt_pk_bf16_f32 v0, v0, v0
	ds_write_b16 v64, v0 offset:7392
	v_fma_f32 v1, v162, v190, v166
	v_fmac_f32_e32 v1, v163, v191
	v_fmac_f32_e32 v1, v164, v223
	v_fmac_f32_e32 v1, v165, v250
	v_cvt_pk_bf16_f32 v1, v1, v1
	ds_write_b16 v64, v1 offset:7920
	global_load_ushort v4, v[2:3], off offset:-1024
	global_load_ushort v5, v[2:3], off
	global_load_ushort v167, v[2:3], off offset:1024
	global_load_ushort v168, v[2:3], off offset:2048
	global_load_ushort v169, v[2:3], off offset:3072
	v_lshl_add_u64 v[2:3], v[2:3], 0, s[30:31]
	global_load_ushort v170, v[2:3], off offset:-4096
	global_load_ushort v171, v[2:3], off offset:-3072
	global_load_ushort v172, v[2:3], off offset:-2048
	global_load_ushort v173, v[2:3], off offset:-1024
	global_load_ushort v178, v[2:3], off
	global_load_ushort v179, v[2:3], off offset:1024
	global_load_ushort v180, v[2:3], off offset:2048
	global_load_ushort v181, v[2:3], off offset:3072
	v_lshl_add_u64 v[2:3], v[2:3], 0, s[30:31]
	global_load_ushort v188, v[2:3], off offset:-4096
	global_load_ushort v189, v[2:3], off offset:-3072
	global_load_ushort v190, v[2:3], off offset:-2048
	s_waitcnt vmcnt(0)
; __device__ __forceinline__ bf16_t f2bf(float f) { return (bf16_t)(cvt_pk_bf16(f, 0.f) & 0xffffu); }
; __device__ __forceinline__ float bf2f(bf16_t b) { return __uint_as_float(((unsigned)b) << 16); }
; template <bool FINAL>
; __device__ __forceinline__ void lru_item(const Ctx& C, int l, int item) {
;     ...
;         for (int k8 = 0; k8 < 4; ++k8) { float xn[8];
; #pragma unroll
;             for (int k = 0; k < 8; ++k) { const int t = t0 + k8 * 8 + k + 1; xn[k] = (t < SEQ) ? bf2f(colp[(size_t)t * 512]) : 0.f; }
; #pragma unroll
;             for (int k = 0; k < 8; ++k) { xc[(tl0 + k8 * 8 + k) * XCP + ch] = f2bf(cb + w0 * xm2 + w1 * xm1 + w2 * x0 + w3 * xn[k]); xm2 = xm1; xm1 = x0; x0 = xn[k]; } }
	v_cndmask_b32_e64 v190, v190, 0, s[0:1]
	v_lshlrev_b32_e32 v4, 16, v4
	v_lshlrev_b32_e32 v5, 16, v5
	v_lshlrev_b32_e32 v167, 16, v167
	v_lshlrev_b32_e32 v168, 16, v168
	v_lshlrev_b32_e32 v169, 16, v169
	v_lshlrev_b32_e32 v170, 16, v170
	v_lshlrev_b32_e32 v171, 16, v171
	v_lshlrev_b32_e32 v172, 16, v172
	v_lshlrev_b32_e32 v173, 16, v173
	v_lshlrev_b32_e32 v178, 16, v178
	v_lshlrev_b32_e32 v179, 16, v179
	v_lshlrev_b32_e32 v180, 16, v180
	v_lshlrev_b32_e32 v181, 16, v181
	v_lshlrev_b32_e32 v188, 16, v188
	v_lshlrev_b32_e32 v189, 16, v189
	v_lshlrev_b32_e32 v190, 16, v190
	v_fma_f32 v0, v162, v191, v166
	v_fmac_f32_e32 v0, v163, v223
	v_fmac_f32_e32 v0, v164, v250
	v_fmac_f32_e32 v0, v165, v4
	v_cvt_pk_bf16_f32 v0, v0, v0
	ds_write_b16 v64, v0 offset:8448
	v_fma_f32 v1, v162, v223, v166
	v_fmac_f32_e32 v1, v163, v250
	v_fmac_f32_e32 v1, v164, v4
	v_fmac_f32_e32 v1, v165, v5
	v_cvt_pk_bf16_f32 v1, v1, v1
	ds_write_b16 v64, v1 offset:8976
	v_fma_f32 v0, v162, v250, v166
	v_fmac_f32_e32 v0, v163, v4
	v_fmac_f32_e32 v0, v164, v5
	v_fmac_f32_e32 v0, v165, v167
	v_cvt_pk_bf16_f32 v0, v0, v0
	ds_write_b16 v64, v0 offset:9504
	v_fma_f32 v1, v162, v4, v166
	v_fmac_f32_e32 v1, v163, v5
	v_fmac_f32_e32 v1, v164, v167
	v_fmac_f32_e32 v1, v165, v168
	v_cvt_pk_bf16_f32 v1, v1, v1
	ds_write_b16 v64, v1 offset:10032
	v_fma_f32 v0, v162, v5, v166
	v_fmac_f32_e32 v0, v163, v167
	v_fmac_f32_e32 v0, v164, v168
	v_fmac_f32_e32 v0, v165, v169
	v_cvt_pk_bf16_f32 v0, v0, v0
	ds_write_b16 v64, v0 offset:10560
	v_fma_f32 v1, v162, v167, v166
	v_fmac_f32_e32 v1, v163, v168
	v_fmac_f32_e32 v1, v164, v169
	v_fmac_f32_e32 v1, v165, v170
	v_cvt_pk_bf16_f32 v1, v1, v1
	ds_write_b16 v64, v1 offset:11088
	v_fma_f32 v0, v162, v168, v166
	v_fmac_f32_e32 v0, v163, v169
	v_fmac_f32_e32 v0, v164, v170
	v_fmac_f32_e32 v0, v165, v171
	v_cvt_pk_bf16_f32 v0, v0, v0
	ds_write_b16 v64, v0 offset:11616
	v_fma_f32 v1, v162, v169, v166
	v_fmac_f32_e32 v1, v163, v170
	v_fmac_f32_e32 v1, v164, v171
	v_fmac_f32_e32 v1, v165, v172
	v_cvt_pk_bf16_f32 v1, v1, v1
	ds_write_b16 v64, v1 offset:12144
	v_fma_f32 v0, v162, v170, v166
	v_fmac_f32_e32 v0, v163, v171
	v_fmac_f32_e32 v0, v164, v172
	v_fmac_f32_e32 v0, v165, v173
	v_cvt_pk_bf16_f32 v0, v0, v0
	ds_write_b16 v64, v0 offset:12672
	v_fma_f32 v1, v162, v171, v166
	v_fmac_f32_e32 v1, v163, v172
	v_fmac_f32_e32 v1, v164, v173
	v_fmac_f32_e32 v1, v165, v178
	v_cvt_pk_bf16_f32 v1, v1, v1
	ds_write_b16 v64, v1 offset:13200
	v_fma_f32 v0, v162, v172, v166
	v_fmac_f32_e32 v0, v163, v173
	v_fmac_f32_e32 v0, v164, v178
	v_fmac_f32_e32 v0, v165, v179
	v_cvt_pk_bf16_f32 v0, v0, v0
	ds_write_b16 v64, v0 offset:13728
	v_fma_f32 v1, v162, v173, v166
	v_fmac_f32_e32 v1, v163, v178
	v_fmac_f32_e32 v1, v164, v179
	v_fmac_f32_e32 v1, v165, v180
	v_cvt_pk_bf16_f32 v1, v1, v1
	ds_write_b16 v64, v1 offset:14256
	v_fma_f32 v0, v162, v178, v166
	v_fmac_f32_e32 v0, v163, v179
	v_fmac_f32_e32 v0, v164, v180
	v_fmac_f32_e32 v0, v165, v181
	v_cvt_pk_bf16_f32 v0, v0, v0
	ds_write_b16 v64, v0 offset:14784
	v_fma_f32 v1, v162, v179, v166
	v_fmac_f32_e32 v1, v163, v180
	v_fmac_f32_e32 v1, v164, v181
	v_fmac_f32_e32 v1, v165, v188
	v_cvt_pk_bf16_f32 v1, v1, v1
	ds_write_b16 v64, v1 offset:15312
	v_fma_f32 v0, v162, v180, v166
	v_fmac_f32_e32 v0, v163, v181
	v_fmac_f32_e32 v0, v164, v188
	v_fmac_f32_e32 v0, v165, v189
	v_cvt_pk_bf16_f32 v0, v0, v0
	ds_write_b16 v64, v0 offset:15840
	v_fma_f32 v1, v162, v181, v166
	v_fmac_f32_e32 v1, v163, v188
	v_fmac_f32_e32 v1, v164, v189
	v_fmac_f32_e32 v1, v165, v190
	v_cvt_pk_bf16_f32 v1, v1, v1
	ds_write_b16 v64, v1 offset:16368
